# pool_z fused into the pool GEMM phase: each unit owner computes the four z tiles its own GEMM unit consumes, so the grid barrier between the two phases becomes a workgroup barrier
# speedup vs baseline: 1.0110x; 1.0110x over previous
.Lxbn8_end:
.LBB0_1636:
	s_or_b64 exec, exec, s[12:13]
	s_mov_b64 s[12:13], s[0:1]
	s_waitcnt lgkmcnt(0)
	v_mov_b32_e32 v0, v170
	s_barrier
	s_mov_b64 s[14:15], exec
	s_load_dwordx2 s[12:13], s[0:1], 0xe8
	v_and_b32_e32 v0, 63, v170
	v_lshlrev_b32_e32 v1, 4, v0
	v_readfirstlane_b32 s34, v170
	s_lshr_b32 s34, s34, 6
	s_waitcnt lgkmcnt(0)
	s_add_u32 s16, s12, 0x46bc000
	s_addc_u32 s17, s13, 0
	s_add_u32 s18, s12, 0x76bc000
	s_addc_u32 s19, s13, 0
	s_add_u32 s20, s12, 0x780000
	s_addc_u32 s21, s13, 0
	s_add_u32 s22, s12, 0x2ebc000
	s_addc_u32 s23, s13, 0
	s_cmpk_gt_i32 s2, 0xbf
	s_cbranch_scc1 .Lpz_end
	s_and_b32 s24, s2, 7
	s_mul_i32 s24, s24, 24
	s_lshr_b32 s40, s2, 3
	s_add_i32 s24, s24, s40
	s_lshr_b32 s40, s24, 5
	s_lshl_b32 s40, s40, 3
	s_and_b32 s41, s24, 7
	s_add_i32 s40, s40, s41
	s_bfe_u32 s41, s24, 0x20003
	s_lshl_b32 s24, s40, 4
	s_add_i32 s24, s24, s41
	s_and_b32 s26, s24, 3
	s_lshr_b32 s28, s24, 2
	s_lshl_b32 s28, s28, 6
	s_lshl_b32 s27, 1, s26
	s_lshl_b32 s35, s27, 1
	s_add_i32 s35, s35, 64
	s_cmp_lt_u32 s28, 0x1000
	s_cbranch_scc0 .Lpza_lat
	s_and_b32 s29, s28, 0xffffff00
	s_movk_i32 s30, 0x100
	s_mov_b32 s45, 30
	s_branch .Lpza_seq

.Lpzb_filled:
	s_lshl_b32 s41, s34, 3
	s_add_i32 s41, s41, s31
	s_sub_i32 s41, s41, s27
	v_add_u32_e32 v3, s41, v0
	v_cmp_le_i32_e64 s[36:37], 0, v3
	v_cmp_gt_i32_e64 s[12:13], s30, v3
	s_and_b64 s[36:37], s[36:37], s[12:13]
	v_cndmask_b32_e64 v5, 0, v14, s[36:37]
	s_lshl_b32 s41, s34, 3
	s_add_i32 s41, s41, 4
	s_add_i32 s41, s41, s31
	s_sub_i32 s41, s41, s27
	v_add_u32_e32 v3, s41, v0
	v_cmp_le_i32_e64 s[36:37], 0, v3
	v_cmp_gt_i32_e64 s[12:13], s30, v3
	s_and_b64 s[36:37], s[36:37], s[12:13]
	v_cndmask_b32_e64 v6, 0, v15, s[36:37]
	v_mov_b32_e32 v7, v16
	v_mov_b32_e32 v8, v17
	v_mov_b32_e32 v10, v18
	v_mov_b32_e32 v11, v19
	v_mov_b32_e32 v12, v20
	v_mov_b32_e32 v13, v21
	s_mov_b32 s25, s26
	s_waitcnt lgkmcnt(0)
	s_barrier
	s_add_i32 s24, s24, 4
	s_bfe_u32 s41, s24, 0x20002
	s_cmp_lg_u32 s41, 0
	s_cbranch_scc0 .Lpz_norq
	s_and_b32 s26, s24, 3
	s_lshr_b32 s28, s24, 2
	s_lshl_b32 s28, s28, 6
	s_lshl_b32 s27, 1, s26
	s_lshl_b32 s35, s27, 1
	s_add_i32 s35, s35, 64
	s_cmp_lt_u32 s28, 0x1000
	s_cbranch_scc0 .Lpzc_lat
	s_and_b32 s29, s28, 0xffffff00
	s_movk_i32 s30, 0x100
	s_mov_b32 s45, 30
	s_branch .Lpzc_seq

.Lpz_next:
	s_barrier
	s_bfe_u32 s41, s24, 0x20002
	s_cmp_lg_u32 s41, 0
	s_cbranch_scc1 .Lpz_tile
.Lpz_end:
	s_mov_b64 exec, s[14:15]
.LBB0_1767:
	s_or_b64 exec, exec, s[14:15]
	s_mov_b64 s[20:21], s[0:1]
	s_waitcnt vmcnt(0) lgkmcnt(0)
	s_barrier
	s_load_dwordx2 s[14:15], s[20:21], 0xe8
	v_mov_b32_e32 v8, v170
	s_waitcnt lgkmcnt(0)
	s_add_u32 s18, s14, 0x46bc000
	s_addc_u32 s19, s15, 0
	s_add_u32 s16, s14, 0x2ebc000
	s_addc_u32 s17, s15, 0
	s_and_b64 vcc, exec, s[10:11]
	v_readfirstlane_b32 s45, v8
	s_cbranch_vccnz .LBB0_1835
	v_lshlrev_b32_e32 v0, 4, v8
	v_add_u32_e32 v1, 0x2000, v0
	v_ashrrev_i32_e32 v2, 31, v1
	v_lshrrev_b32_e32 v2, 22, v2
	v_add_u32_e32 v2, v1, v2
	v_ashrrev_i32_e32 v2, 10, v2
	v_mul_i32_i24_e32 v4, 0x400, v2
	v_sub_u32_e32 v1, v1, v4
	v_lshrrev_b32_e32 v4, 4, v1
	v_bitop3_b32 v1, v4, v1, 32 bitop3:0x6c
	v_ashrrev_i32_e32 v4, 31, v1
	v_lshrrev_b32_e32 v4, 26, v4
	v_add_u32_e32 v4, v1, v4
	v_lshlrev_b32_e32 v3, 5, v2
	v_ashrrev_i32_e32 v5, 6, v4
	v_and_b32_e32 v4, 0xc0, v4
	v_lshlrev_b32_e32 v2, 3, v2
	v_sub_u32_e32 v1, v1, v4
	v_mov_b32_e32 v4, 1
	v_and_b32_e32 v2, -16, v2
	v_and_b32_e32 v3, 32, v3
	v_ashrrev_i16_sdwa v1, v4, sext(v1) dst_sel:DWORD dst_unused:UNUSED_PAD src0_sel:DWORD src1_sel:BYTE_0
	v_add_u32_e32 v2, v5, v2
	v_add_u32_sdwa v1, v3, sext(v1) dst_sel:DWORD dst_unused:UNUSED_PAD src0_sel:DWORD src1_sel:WORD_0
	v_lshlrev_b32_e32 v3, 9, v2
	v_lshl_add_u32 v128, v1, 1, v3
	s_movk_i32 s12, 0x600
	s_add_u32 s47, s14, 0xe3c000
	v_mad_u64_u32 v[130:131], s[22:23], v2, s12, v[128:129]
	s_addc_u32 s72, s15, 0
	s_lshr_b32 s22, s3, 29
	v_bfe_i32 v3, v8, 27, 1
	s_add_i32 s22, s2, s22
	v_lshrrev_b32_e32 v3, 22, v3
	s_ashr_i32 s23, s22, 3
	s_and_b32 s22, s22, -8
	v_add_u32_e32 v3, v0, v3
	s_sub_i32 s22, s2, s22
	v_and_b32_e32 v3, 0xfffffc00, v3
	s_lshr_b32 s25, s22, 31
	v_sub_u32_e32 v0, v0, v3
	s_or_b32 s25, s25, 24
	v_lshrrev_b32_e32 v3, 4, v0
	s_mul_i32 s22, s25, s22
	v_ashrrev_i32_e32 v1, 31, v8
	v_bitop3_b32 v3, v3, v0, 32 bitop3:0x6c
	v_ashrrev_i32_e32 v0, 31, v0
	s_add_i32 s22, s22, s23
	v_lshrrev_b32_e32 v1, 26, v1
	v_lshrrev_b32_e32 v0, 26, v0
	s_ashr_i32 s23, s22, 31
	v_add_u32_e32 v1, v8, v1
	v_add_u32_e32 v0, v3, v0
	s_lshr_b32 s23, s23, 27
	v_ashrrev_i32_e32 v1, 6, v1
	v_ashrrev_i32_e32 v0, 6, v0
	s_add_i32 s23, s22, s23
	v_lshlrev_b32_e32 v2, 5, v1
	v_mul_i32_i24_e32 v5, 64, v0
	v_lshlrev_b32_e32 v1, 3, v1
	s_ashr_i32 s23, s23, 5
	v_sub_u32_e32 v3, v3, v5
	v_and_b32_e32 v1, -16, v1
	s_lshl_b32 s25, s23, 3
	v_and_b32_e32 v2, 32, v2
	v_ashrrev_i16_sdwa v3, v4, sext(v3) dst_sel:DWORD dst_unused:UNUSED_PAD src0_sel:DWORD src1_sel:BYTE_0
	v_add_u32_e32 v0, v0, v1
	s_sub_i32 s26, 48, s25
	s_lshl_b32 s23, s23, 5
	v_add_u32_sdwa v2, v2, sext(v3) dst_sel:DWORD dst_unused:UNUSED_PAD src0_sel:DWORD src1_sel:WORD_0
	v_lshlrev_b32_e32 v1, 9, v0
	s_min_u32 s26, s26, 8
	s_sub_i32 s27, s22, s23
	v_lshl_add_u32 v132, v2, 1, v1
	s_sext_i32_i8 s28, s27
	v_cvt_f32_ubyte0_e32 v2, s26
	v_cvt_f32_i32_e32 v1, s28
	v_rcp_iflag_f32_e32 v3, v2
	v_mad_u64_u32 v[134:135], s[22:23], v0, s12, v[132:133]
	s_ashr_i32 s24, s45, 6
	v_mul_f32_e32 v0, v1, v3
	v_trunc_f32_e32 v0, v0
	v_fma_f32 v1, -v0, v2, v1
	v_cvt_i32_f32_e32 v0, v0
	s_ashr_i32 s12, s28, 30
	s_ashr_i32 s13, s45, 8
	s_lshl_b32 s73, s24, 10
	s_or_b32 s12, s12, 1
	v_cmp_ge_f32_e64 s[22:23], |v1|, v2
	s_and_b64 s[22:23], s[22:23], exec
	s_cselect_b32 s12, s12, 0
	v_readfirstlane_b32 s22, v0
	s_add_i32 s12, s22, s12
	s_mul_i32 s22, s12, s26
	s_sub_i32 s22, s27, s22
	s_sext_i32_i8 s22, s22
	s_add_i32 s22, s25, s22
	s_ashr_i32 s23, s22, 31
	s_bfe_i64 s[28:29], s[12:13], 0x80000
	s_lshl_b64 s[26:27], s[22:23], 19
	s_lshl_b64 s[30:31], s[28:29], 9
	s_lshl_b64 s[28:29], s[28:29], 17
	s_add_u32 s54, s47, s28
	s_addc_u32 s55, s72, s29
	s_add_i32 s48, s73, 0
	s_add_i32 m0, s48, 0x10000
	v_mov_b32_e32 v133, 0
	global_load_lds_dwordx4 v132, s[54:55]
	s_add_i32 m0, s48, 0x12000
	s_add_u32 s23, s16, s26
	s_addc_u32 s25, s17, s27
	s_add_u32 s56, s23, s30
	global_load_lds_dwordx4 v128, s[54:55]
	s_addc_u32 s57, s25, s31
	s_mov_b32 m0, s48
	s_add_i32 s75, s48, 0x2000
	global_load_lds_dwordx4 v134, s[56:57]
	s_mov_b32 m0, s75
	s_add_u32 s26, s54, 0x10000
	global_load_lds_dwordx4 v130, s[56:57]
	s_addc_u32 s27, s55, 0
	s_add_i32 m0, s48, 0x14000
	v_writelane_b32 v234, s4, 2
	global_load_lds_dwordx4 v132, s[26:27]
	s_add_i32 m0, s48, 0x16000
	v_mov_b32_e32 v129, v133
	global_load_lds_dwordx4 v128, s[26:27]
	s_add_u32 s26, s56, 0x40000
	s_addc_u32 s27, s57, 0
	s_add_i32 s76, s48, 0x4000
	s_mov_b32 m0, s76
	s_add_i32 s77, s48, 0x6000
	global_load_lds_dwordx4 v134, s[26:27]
	s_mov_b32 m0, s77
	v_mov_b32_e32 v135, v133
	global_load_lds_dwordx4 v130, s[26:27]
	v_mov_b32_e32 v131, v133
	v_writelane_b32 v234, s5, 3
	s_mov_b64 s[4:5], s[38:39]
	s_mov_b32 s38, s46
	s_mov_b64 s[8:9], s[10:11]
	s_mov_b64 s[10:11], s[6:7]
	s_mov_b64 s[6:7], s[88:89]
	s_mov_b32 s46, s90
	s_mov_b32 s23, 0
	v_lshl_add_u64 v[6:7], s[54:55], 0, v[132:133]
	v_lshl_add_u64 v[4:5], s[54:55], 0, v[128:129]
	v_lshl_add_u64 v[2:3], s[56:57], 0, v[134:135]
	s_cmp_lg_u32 s13, 1
	v_lshl_add_u64 v[0:1], s[56:57], 0, v[130:131]
	s_cbranch_scc1 .LBB0_1822
	s_barrier
